# best + SwiGLU K-loop load segments rewritten: SGPR-base LDS-DMA addressing and hoisted ds_read base (no VALU in load segments)
# speedup vs baseline: 1.0170x; 1.0041x over previous
; #define PG8_STAGE(bufoff, gbase, voff) do { _Pragma("unroll") for (int _i = 0; _i < 2; ++_i) \
;         __builtin_amdgcn_global_load_lds((const unsigned*)((const char*)(gbase) + (voff)[_i]), (PG8_LAS unsigned*)(lds + (bufoff) + ldsw + _i * 8192), 16, 0, 0); } while (0)
; #define PG8_LDA(dst, b, h) do { _Pragma("unroll") for (int m = 0; m < 4; ++m) _Pragma("unroll") for (int k = 0; k < 2; ++k) dst[m][k] = *(const PG8_LAS bf16x8*)(lds + PG8_SA(b, h) + aoff + m * 2048 + k * 1024); } while (0)
; #define PG8_LDB(dst, b, h) do { _Pragma("unroll") for (int n = 0; n < 2; ++n) _Pragma("unroll") for (int k = 0; k < 2; ++k) dst[n][k] = *(const PG8_LAS bf16x8*)(lds + PG8_SB(b, h) + boff + n * 2048 + k * 1024); } while (0)
; #define PG8_MMA(ai, bj, At, Bt) do { __builtin_amdgcn_s_setprio(1); _Pragma("unroll") for (int m = 0; m < 4; ++m) _Pragma("unroll") for (int n = 0; n < 2; ++n) _Pragma("unroll") for (int k = 0; k < 2; ++k) \
;         acc[ai][bj][m][n] = __builtin_amdgcn_mfma_f32_16x16x32_bf16(Bt[n][k], At[m][k], acc[ai][bj][m][n], 0, 0, 0); __builtin_amdgcn_s_setprio(0); } while (0)
; #define PG8_WAIT_V(n) asm volatile("s_waitcnt vmcnt(" #n ")" ::: "memory")
; #define PG8_WAIT_L(n) asm volatile("s_waitcnt lgkmcnt(" #n ")" ::: "memory")
; #define PG8_BAR __builtin_amdgcn_s_barrier()
; #define PG8_SCHED __builtin_amdgcn_sched_barrier(0)
; template <class Epi, class Sched, bool ALIGN_EPI = false, bool SP2 = false>
; __device__ __forceinline__ void gemm_phase(PG8_LAS unsigned char* lds, const Gemm g, const Sched& S, const Epi& E) {
;     ...
;             PG8_LDB(B0, 0, 0); PG8_LDB(B1, 0, 1); PG8_SCHED; PG8_LDA(At, 0, 0); PG8_STAGE(PG8_SA(1, 1), a1 + hstep, voffA);
;             PG8_WAIT_V(8); PG8_WAIT_L(0); PG8_BAR; PG8_MMA(0, 0, At, B0); PG8_MMA(0, 1, At, B1); PG8_BAR; PG8_SCHED;
;     ...
; #pragma unroll
;         for (int a = 0; a < 2; ++a)
; #pragma unroll
;             for (int b = 0; b < 2; ++b)
; #pragma unroll
;                 for (int m = 0; m < 4; ++m)
; #pragma unroll
;                     for (int n = 0; n < 2; ++n) acc[a][b][m][n] = (f32x4){0.f, 0.f, 0.f, 0.f};
;         cur = nxt; cA = nA; cB = nB; ++ui;
.LBB0_408:
	s_ashr_i32 s11, s10, 31
	s_lshl_b64 s[12:13], s[10:11], 19
	s_add_u32 s12, s30, s12
	s_addc_u32 s13, s31, s13
	s_and_b64 s[18:19], s[4:5], exec
	s_cselect_b32 s11, s13, s23
	s_cselect_b32 s53, s12, s22
	s_ashr_i32 s9, s8, 31
	s_lshl_b64 s[18:19], s[8:9], 19
	s_add_u32 s18, s37, s18
	s_addc_u32 s19, s44, s19
	s_and_b64 s[26:27], s[4:5], exec
	s_cselect_b32 s9, s19, s25
	s_cselect_b32 s54, s18, s24
	s_add_u32 s55, s24, 0x100
	v_mov_b64_e32 v[2:3], 0
	v_mov_b64_e32 v[4:5], 0
	v_mov_b64_e32 v[6:7], 0
	v_mov_b64_e32 v[8:9], 0
	v_mov_b64_e32 v[10:11], 0
	v_mov_b64_e32 v[12:13], 0
	v_mov_b64_e32 v[14:15], 0
	v_mov_b64_e32 v[16:17], 0
	v_mov_b64_e32 v[18:19], 0
	v_mov_b64_e32 v[20:21], 0
	v_mov_b64_e32 v[22:23], 0
	v_mov_b64_e32 v[24:25], 0
	v_mov_b64_e32 v[26:27], 0
	v_mov_b64_e32 v[28:29], 0
	v_mov_b64_e32 v[30:31], 0
	v_mov_b64_e32 v[32:33], 0
	v_mov_b64_e32 v[34:35], 0
	v_mov_b64_e32 v[36:37], 0
	v_mov_b64_e32 v[38:39], 0
	v_mov_b64_e32 v[40:41], 0
	v_mov_b64_e32 v[42:43], 0
	v_mov_b64_e32 v[44:45], 0
	v_mov_b64_e32 v[46:47], 0
	v_mov_b64_e32 v[48:49], 0
	v_mov_b64_e32 v[50:51], 0
	v_mov_b64_e32 v[52:53], 0
	v_mov_b64_e32 v[54:55], 0
	v_mov_b64_e32 v[56:57], 0
	v_mov_b64_e32 v[58:59], 0
	v_mov_b64_e32 v[60:61], 0
	v_mov_b64_e32 v[62:63], 0
	v_mov_b64_e32 v[64:65], 0
	v_mov_b64_e32 v[66:67], 0
	v_mov_b64_e32 v[68:69], 0
	v_mov_b64_e32 v[70:71], 0
	v_mov_b64_e32 v[72:73], 0
	v_mov_b64_e32 v[74:75], 0
	v_mov_b64_e32 v[76:77], 0
	v_mov_b64_e32 v[78:79], 0
	v_mov_b64_e32 v[80:81], 0
	v_mov_b64_e32 v[82:83], 0
	v_mov_b64_e32 v[84:85], 0
	v_mov_b64_e32 v[86:87], 0
	v_mov_b64_e32 v[88:89], 0
	v_mov_b64_e32 v[90:91], 0
	v_mov_b64_e32 v[92:93], 0
	v_mov_b64_e32 v[94:95], 0
	v_mov_b64_e32 v[96:97], 0
	v_mov_b64_e32 v[98:99], 0
	v_mov_b64_e32 v[100:101], 0
	v_mov_b64_e32 v[102:103], 0
	v_mov_b64_e32 v[104:105], 0
	v_mov_b64_e32 v[106:107], 0
	v_mov_b64_e32 v[108:109], 0
	v_mov_b64_e32 v[110:111], 0
	v_mov_b64_e32 v[112:113], 0
	v_mov_b64_e32 v[114:115], 0
	v_mov_b64_e32 v[116:117], 0
	v_mov_b64_e32 v[118:119], 0
	v_mov_b64_e32 v[120:121], 0
	v_mov_b64_e32 v[122:123], 0
	v_mov_b64_e32 v[124:125], 0
	v_mov_b64_e32 v[126:127], 0
	v_mov_b64_e32 v[128:129], 0
	s_addc_u32 s56, s25, 0
	s_mov_b32 s57, -2
	v_add_u32_e32 v145, s76, v142
.LBB0_409:
	s_add_u32 s24, s22, 0x8000
	s_addc_u32 s25, s23, 0
	s_cmp_eq_u32 s57, 12
	s_cselect_b32 s42, s53, s24
	s_cselect_b32 s43, s11, s25
	s_cselect_b32 s40, s54, s55
	s_cselect_b32 s41, s9, s56
	s_add_u32 s26, s42, 0x4000
	s_addc_u32 s27, s43, 0
	ds_read_b128 v[146:149], v145
	ds_read_b128 v[150:153], v145 offset:1024
	ds_read_b128 v[160:163], v145 offset:2048
	ds_read_b128 v[164:167], v145 offset:3072
	ds_read_b128 v[168:171], v145 offset:16384
	ds_read_b128 v[172:175], v145 offset:17408
	ds_read_b128 v[176:179], v145 offset:18432
	ds_read_b128 v[180:183], v145 offset:19456
	s_add_i32 m0, s45, 0xc000
	ds_read_b128 v[184:187], v144
	ds_read_b128 v[188:191], v144 offset:1024
	ds_read_b128 v[206:209], v144 offset:2048
	ds_read_b128 v[210:213], v144 offset:3072
	ds_read_b128 v[214:217], v144 offset:4096
	ds_read_b128 v[218:221], v144 offset:5120
	ds_read_b128 v[222:225], v144 offset:6144
	ds_read_b128 v[226:229], v144 offset:7168
	global_load_lds_dwordx4 v140, s[22:23]
	s_add_i32 m0, s45, 0xe000
	s_nop 0
	global_load_lds_dwordx4 v138, s[22:23]
	s_waitcnt vmcnt(8)
	s_waitcnt lgkmcnt(0)
	s_barrier
	v_mfma_f32_16x16x32_bf16 v[126:129], v[146:149], v[184:187], v[126:129]
	v_mfma_f32_16x16x32_bf16 v[126:129], v[150:153], v[188:191], v[126:129]
	v_mfma_f32_16x16x32_bf16 v[118:121], v[164:167], v[188:191], v[118:121]
	v_mfma_f32_16x16x32_bf16 v[118:121], v[160:163], v[184:187], v[118:121]
	v_mfma_f32_16x16x32_bf16 v[102:105], v[160:163], v[206:209], v[102:105]
	v_mfma_f32_16x16x32_bf16 v[102:105], v[164:167], v[210:213], v[102:105]
	v_mfma_f32_16x16x32_bf16 v[110:113], v[150:153], v[210:213], v[110:113]
	v_mfma_f32_16x16x32_bf16 v[110:113], v[146:149], v[206:209], v[110:113]
	v_mfma_f32_16x16x32_bf16 v[94:97], v[146:149], v[214:217], v[94:97]
	v_mfma_f32_16x16x32_bf16 v[94:97], v[150:153], v[218:221], v[94:97]
	v_mfma_f32_16x16x32_bf16 v[86:89], v[164:167], v[218:221], v[86:89]
	v_mfma_f32_16x16x32_bf16 v[86:89], v[160:163], v[214:217], v[86:89]
	v_mfma_f32_16x16x32_bf16 v[70:73], v[160:163], v[222:225], v[70:73]
	v_mfma_f32_16x16x32_bf16 v[70:73], v[164:167], v[226:229], v[70:73]
	v_mfma_f32_16x16x32_bf16 v[78:81], v[150:153], v[226:229], v[78:81]
	v_mfma_f32_16x16x32_bf16 v[78:81], v[146:149], v[222:225], v[78:81]
	v_mfma_f32_16x16x32_bf16 v[122:125], v[168:171], v[184:187], v[122:125]
	v_mfma_f32_16x16x32_bf16 v[122:125], v[172:175], v[188:191], v[122:125]
	v_mfma_f32_16x16x32_bf16 v[114:117], v[180:183], v[188:191], v[114:117]
	v_mfma_f32_16x16x32_bf16 v[114:117], v[176:179], v[184:187], v[114:117]
	v_mfma_f32_16x16x32_bf16 v[98:101], v[176:179], v[206:209], v[98:101]
	v_mfma_f32_16x16x32_bf16 v[98:101], v[180:183], v[210:213], v[98:101]
	v_mfma_f32_16x16x32_bf16 v[106:109], v[172:175], v[210:213], v[106:109]
	v_mfma_f32_16x16x32_bf16 v[106:109], v[168:171], v[206:209], v[106:109]
	v_mfma_f32_16x16x32_bf16 v[90:93], v[168:171], v[214:217], v[90:93]
	v_mfma_f32_16x16x32_bf16 v[90:93], v[172:175], v[218:221], v[90:93]
	v_mfma_f32_16x16x32_bf16 v[82:85], v[180:183], v[218:221], v[82:85]
	v_mfma_f32_16x16x32_bf16 v[82:85], v[176:179], v[214:217], v[82:85]
	v_mfma_f32_16x16x32_bf16 v[66:69], v[176:179], v[222:225], v[66:69]
	v_mfma_f32_16x16x32_bf16 v[66:69], v[180:183], v[226:229], v[66:69]
	v_mfma_f32_16x16x32_bf16 v[74:77], v[172:175], v[226:229], v[74:77]
	v_mfma_f32_16x16x32_bf16 v[74:77], v[168:171], v[222:225], v[74:77]
	s_barrier
; #define PG8_STAGE(bufoff, gbase, voff) do { _Pragma("unroll") for (int _i = 0; _i < 2; ++_i) \
;         __builtin_amdgcn_global_load_lds((const unsigned*)((const char*)(gbase) + (voff)[_i]), (PG8_LAS unsigned*)(lds + (bufoff) + ldsw + _i * 8192), 16, 0, 0); } while (0)
; #define PG8_LDA(dst, b, h) do { _Pragma("unroll") for (int m = 0; m < 4; ++m) _Pragma("unroll") for (int k = 0; k < 2; ++k) dst[m][k] = *(const PG8_LAS bf16x8*)(lds + PG8_SA(b, h) + aoff + m * 2048 + k * 1024); } while (0)
; #define PG8_LDB(dst, b, h) do { _Pragma("unroll") for (int n = 0; n < 2; ++n) _Pragma("unroll") for (int k = 0; k < 2; ++k) dst[n][k] = *(const PG8_LAS bf16x8*)(lds + PG8_SB(b, h) + boff + n * 2048 + k * 1024); } while (0)
; #define PG8_MMA(ai, bj, At, Bt) do { __builtin_amdgcn_s_setprio(1); _Pragma("unroll") for (int m = 0; m < 4; ++m) _Pragma("unroll") for (int n = 0; n < 2; ++n) _Pragma("unroll") for (int k = 0; k < 2; ++k) \
;         acc[ai][bj][m][n] = __builtin_amdgcn_mfma_f32_16x16x32_bf16(Bt[n][k], At[m][k], acc[ai][bj][m][n], 0, 0, 0); __builtin_amdgcn_s_setprio(0); } while (0)
; #define PG8_WAIT_V(n) asm volatile("s_waitcnt vmcnt(" #n ")" ::: "memory")
; #define PG8_WAIT_L(n) asm volatile("s_waitcnt lgkmcnt(" #n ")" ::: "memory")
; #define PG8_BAR __builtin_amdgcn_s_barrier()
; #define PG8_SCHED __builtin_amdgcn_sched_barrier(0)
; template <class Epi, class Sched, bool ALIGN_EPI = false, bool SP2 = false>
; __device__ __forceinline__ void gemm_phase(PG8_LAS unsigned char* lds, const Gemm g, const Sched& S, const Epi& E) {
;     ...
;             PG8_LDA(At, 0, 1); PG8_STAGE(PG8_SB(0, 0), b2, voffB); PG8_STAGE(PG8_SB(0, 1), b2 + hstep, voffB); PG8_STAGE(PG8_SA(0, 0), a2, voffA);
;             PG8_WAIT_V(8); PG8_WAIT_L(0); PG8_BAR; PG8_MMA(1, 0, At, B0); PG8_MMA(1, 1, At, B1); PG8_BAR; PG8_SCHED;
;             PG8_LDB(B0, 1, 0); PG8_LDB(B1, 1, 1); PG8_SCHED; PG8_LDA(At, 1, 0); PG8_STAGE(PG8_SA(0, 1), a2 + hstep, voffA);
	s_add_i32 s58, s76, s29
	s_mov_b32 m0, s58
	ds_read_b128 v[184:187], v144 offset:16384
	ds_read_b128 v[188:191], v144 offset:17408
	ds_read_b128 v[206:209], v144 offset:18432
	ds_read_b128 v[210:213], v144 offset:19456
	ds_read_b128 v[214:217], v144 offset:20480
	ds_read_b128 v[218:221], v144 offset:21504
	ds_read_b128 v[222:225], v144 offset:22528
	ds_read_b128 v[226:229], v144 offset:23552
	global_load_lds_dwordx4 v0, s[40:41]
	s_add_i32 m0, s58, 0x2000
	s_add_u32 s22, s40, 0x40000
	s_addc_u32 s23, s41, 0
	global_load_lds_dwordx4 v130, s[40:41]
	s_add_i32 m0, s58, 0x4000
	s_nop 0
	global_load_lds_dwordx4 v0, s[22:23]
	s_add_i32 m0, s58, 0x6000
	s_nop 0
	global_load_lds_dwordx4 v130, s[22:23]
	s_mov_b32 m0, s45
	s_nop 0
	global_load_lds_dwordx4 v134, s[42:43]
	s_mov_b32 m0, s46
	s_nop 0
	global_load_lds_dwordx4 v132, s[42:43]
	s_waitcnt vmcnt(8)
	s_waitcnt lgkmcnt(0)
	s_barrier
	v_mfma_f32_16x16x32_bf16 v[62:65], v[146:149], v[184:187], v[62:65]
	v_mfma_f32_16x16x32_bf16 v[62:65], v[150:153], v[188:191], v[62:65]
	v_mfma_f32_16x16x32_bf16 v[54:57], v[164:167], v[188:191], v[54:57]
	v_mfma_f32_16x16x32_bf16 v[54:57], v[160:163], v[184:187], v[54:57]
	v_mfma_f32_16x16x32_bf16 v[38:41], v[160:163], v[206:209], v[38:41]
	v_mfma_f32_16x16x32_bf16 v[38:41], v[164:167], v[210:213], v[38:41]
	v_mfma_f32_16x16x32_bf16 v[46:49], v[150:153], v[210:213], v[46:49]
	v_mfma_f32_16x16x32_bf16 v[46:49], v[146:149], v[206:209], v[46:49]
	v_mfma_f32_16x16x32_bf16 v[30:33], v[146:149], v[214:217], v[30:33]
	v_mfma_f32_16x16x32_bf16 v[30:33], v[150:153], v[218:221], v[30:33]
	v_mfma_f32_16x16x32_bf16 v[22:25], v[164:167], v[218:221], v[22:25]
	v_mfma_f32_16x16x32_bf16 v[22:25], v[160:163], v[214:217], v[22:25]
	v_mfma_f32_16x16x32_bf16 v[6:9], v[160:163], v[222:225], v[6:9]
	v_mfma_f32_16x16x32_bf16 v[6:9], v[164:167], v[226:229], v[6:9]
	v_mfma_f32_16x16x32_bf16 v[14:17], v[150:153], v[226:229], v[14:17]
	v_mfma_f32_16x16x32_bf16 v[14:17], v[146:149], v[222:225], v[14:17]
	v_mfma_f32_16x16x32_bf16 v[58:61], v[168:171], v[184:187], v[58:61]
	v_mfma_f32_16x16x32_bf16 v[58:61], v[172:175], v[188:191], v[58:61]
	v_mfma_f32_16x16x32_bf16 v[50:53], v[180:183], v[188:191], v[50:53]
	v_mfma_f32_16x16x32_bf16 v[50:53], v[176:179], v[184:187], v[50:53]
	v_mfma_f32_16x16x32_bf16 v[34:37], v[176:179], v[206:209], v[34:37]
	v_mfma_f32_16x16x32_bf16 v[34:37], v[180:183], v[210:213], v[34:37]
	v_mfma_f32_16x16x32_bf16 v[42:45], v[172:175], v[210:213], v[42:45]
	v_mfma_f32_16x16x32_bf16 v[42:45], v[168:171], v[206:209], v[42:45]
	v_mfma_f32_16x16x32_bf16 v[26:29], v[168:171], v[214:217], v[26:29]
	v_mfma_f32_16x16x32_bf16 v[26:29], v[172:175], v[218:221], v[26:29]
	v_mfma_f32_16x16x32_bf16 v[18:21], v[180:183], v[218:221], v[18:21]
	v_mfma_f32_16x16x32_bf16 v[18:21], v[176:179], v[214:217], v[18:21]
	v_mfma_f32_16x16x32_bf16 v[2:5], v[176:179], v[222:225], v[2:5]
	v_mfma_f32_16x16x32_bf16 v[2:5], v[180:183], v[226:229], v[2:5]
	v_mfma_f32_16x16x32_bf16 v[10:13], v[172:175], v[226:229], v[10:13]
	v_mfma_f32_16x16x32_bf16 v[10:13], v[168:171], v[222:225], v[10:13]
	s_barrier
	ds_read_b128 v[146:149], v145 offset:32768
	ds_read_b128 v[150:153], v145 offset:33792
	ds_read_b128 v[160:163], v145 offset:34816
	ds_read_b128 v[164:167], v145 offset:35840
	ds_read_b128 v[168:171], v145 offset:49152
	ds_read_b128 v[172:175], v145 offset:50176
	ds_read_b128 v[176:179], v145 offset:51200
	ds_read_b128 v[180:183], v145 offset:52224
	s_add_u32 s22, s42, 0x40000
	s_addc_u32 s23, s43, 0
	s_mov_b32 m0, s47
	ds_read_b128 v[184:187], v144 offset:32768
	ds_read_b128 v[188:191], v144 offset:33792
	ds_read_b128 v[206:209], v144 offset:34816
	ds_read_b128 v[210:213], v144 offset:35840
	ds_read_b128 v[214:217], v144 offset:36864
	ds_read_b128 v[218:221], v144 offset:37888
	ds_read_b128 v[222:225], v144 offset:38912
	ds_read_b128 v[226:229], v144 offset:39936
	global_load_lds_dwordx4 v134, s[22:23]
	s_mov_b32 m0, s48
	s_nop 0
	global_load_lds_dwordx4 v132, s[22:23]
	s_waitcnt vmcnt(8)
	s_waitcnt lgkmcnt(0)
	s_barrier
; #define PG8_STAGE(bufoff, gbase, voff) do { _Pragma("unroll") for (int _i = 0; _i < 2; ++_i) \
;         __builtin_amdgcn_global_load_lds((const unsigned*)((const char*)(gbase) + (voff)[_i]), (PG8_LAS unsigned*)(lds + (bufoff) + ldsw + _i * 8192), 16, 0, 0); } while (0)
; #define PG8_LDA(dst, b, h) do { _Pragma("unroll") for (int m = 0; m < 4; ++m) _Pragma("unroll") for (int k = 0; k < 2; ++k) dst[m][k] = *(const PG8_LAS bf16x8*)(lds + PG8_SA(b, h) + aoff + m * 2048 + k * 1024); } while (0)
; #define PG8_MMA(ai, bj, At, Bt) do { __builtin_amdgcn_s_setprio(1); _Pragma("unroll") for (int m = 0; m < 4; ++m) _Pragma("unroll") for (int n = 0; n < 2; ++n) _Pragma("unroll") for (int k = 0; k < 2; ++k) \
;         acc[ai][bj][m][n] = __builtin_amdgcn_mfma_f32_16x16x32_bf16(Bt[n][k], At[m][k], acc[ai][bj][m][n], 0, 0, 0); __builtin_amdgcn_s_setprio(0); } while (0)
; #define PG8_WAIT_V(n) asm volatile("s_waitcnt vmcnt(" #n ")" ::: "memory")
; #define PG8_WAIT_L(n) asm volatile("s_waitcnt lgkmcnt(" #n ")" ::: "memory")
; #define PG8_BAR __builtin_amdgcn_s_barrier()
; #define PG8_SCHED __builtin_amdgcn_sched_barrier(0)
; template <class Epi, class Sched, bool ALIGN_EPI = false, bool SP2 = false>
; __device__ __forceinline__ void gemm_phase(PG8_LAS unsigned char* lds, const Gemm g, const Sched& S, const Epi& E) {
;     ...
;             PG8_WAIT_V(8); PG8_WAIT_L(0); PG8_BAR; PG8_MMA(0, 0, At, B0); PG8_MMA(0, 1, At, B1); PG8_BAR; PG8_SCHED;
;             PG8_LDA(At, 1, 1); PG8_STAGE(PG8_SB(1, 0), b3, voffB); PG8_STAGE(PG8_SB(1, 1), b3 + hstep, voffB); PG8_STAGE(PG8_SA(1, 0), a3, voffA);
;             PG8_WAIT_V(8); PG8_WAIT_L(0); PG8_BAR; PG8_MMA(1, 0, At, B0); PG8_MMA(1, 1, At, B1); PG8_BAR; PG8_SCHED;
	v_mfma_f32_16x16x32_bf16 v[126:129], v[146:149], v[184:187], v[126:129]
	v_mfma_f32_16x16x32_bf16 v[126:129], v[150:153], v[188:191], v[126:129]
	v_mfma_f32_16x16x32_bf16 v[118:121], v[164:167], v[188:191], v[118:121]
	v_mfma_f32_16x16x32_bf16 v[118:121], v[160:163], v[184:187], v[118:121]
	v_mfma_f32_16x16x32_bf16 v[102:105], v[160:163], v[206:209], v[102:105]
	v_mfma_f32_16x16x32_bf16 v[102:105], v[164:167], v[210:213], v[102:105]
	v_mfma_f32_16x16x32_bf16 v[110:113], v[150:153], v[210:213], v[110:113]
	v_mfma_f32_16x16x32_bf16 v[110:113], v[146:149], v[206:209], v[110:113]
	v_mfma_f32_16x16x32_bf16 v[94:97], v[146:149], v[214:217], v[94:97]
	v_mfma_f32_16x16x32_bf16 v[94:97], v[150:153], v[218:221], v[94:97]
	v_mfma_f32_16x16x32_bf16 v[86:89], v[164:167], v[218:221], v[86:89]
	v_mfma_f32_16x16x32_bf16 v[86:89], v[160:163], v[214:217], v[86:89]
	v_mfma_f32_16x16x32_bf16 v[70:73], v[160:163], v[222:225], v[70:73]
	v_mfma_f32_16x16x32_bf16 v[70:73], v[164:167], v[226:229], v[70:73]
	v_mfma_f32_16x16x32_bf16 v[78:81], v[150:153], v[226:229], v[78:81]
	v_mfma_f32_16x16x32_bf16 v[78:81], v[146:149], v[222:225], v[78:81]
	v_mfma_f32_16x16x32_bf16 v[122:125], v[168:171], v[184:187], v[122:125]
	v_mfma_f32_16x16x32_bf16 v[122:125], v[172:175], v[188:191], v[122:125]
	v_mfma_f32_16x16x32_bf16 v[114:117], v[180:183], v[188:191], v[114:117]
	v_mfma_f32_16x16x32_bf16 v[114:117], v[176:179], v[184:187], v[114:117]
	v_mfma_f32_16x16x32_bf16 v[98:101], v[176:179], v[206:209], v[98:101]
	v_mfma_f32_16x16x32_bf16 v[98:101], v[180:183], v[210:213], v[98:101]
	v_mfma_f32_16x16x32_bf16 v[106:109], v[172:175], v[210:213], v[106:109]
	v_mfma_f32_16x16x32_bf16 v[106:109], v[168:171], v[206:209], v[106:109]
	v_mfma_f32_16x16x32_bf16 v[90:93], v[168:171], v[214:217], v[90:93]
	v_mfma_f32_16x16x32_bf16 v[90:93], v[172:175], v[218:221], v[90:93]
	v_mfma_f32_16x16x32_bf16 v[82:85], v[180:183], v[218:221], v[82:85]
	v_mfma_f32_16x16x32_bf16 v[82:85], v[176:179], v[214:217], v[82:85]
	v_mfma_f32_16x16x32_bf16 v[66:69], v[176:179], v[222:225], v[66:69]
	v_mfma_f32_16x16x32_bf16 v[66:69], v[180:183], v[226:229], v[66:69]
	v_mfma_f32_16x16x32_bf16 v[74:77], v[172:175], v[226:229], v[74:77]
	v_mfma_f32_16x16x32_bf16 v[74:77], v[168:171], v[222:225], v[74:77]
	s_barrier
	s_add_u32 s22, s40, 0x80
	s_addc_u32 s23, s41, 0
	s_add_i32 s58, s29, 0x18000
	s_mov_b32 m0, s58
	ds_read_b128 v[184:187], v144 offset:49152
	ds_read_b128 v[188:191], v144 offset:50176
	ds_read_b128 v[206:209], v144 offset:51200
	ds_read_b128 v[210:213], v144 offset:52224
	ds_read_b128 v[214:217], v144 offset:53248
	ds_read_b128 v[218:221], v144 offset:54272
	ds_read_b128 v[222:225], v144 offset:55296
	ds_read_b128 v[226:229], v144 offset:56320
	global_load_lds_dwordx4 v0, s[22:23]
	s_add_i32 m0, s58, 0x2000
	s_add_u32 s40, s22, 0x40000
	s_addc_u32 s41, s23, 0
	global_load_lds_dwordx4 v130, s[22:23]
	s_add_i32 m0, s58, 0x4000
	s_nop 0
	global_load_lds_dwordx4 v0, s[40:41]
	s_add_i32 m0, s58, 0x6000
	s_nop 0
	global_load_lds_dwordx4 v130, s[40:41]
	s_mov_b32 m0, s49
	s_nop 0
	global_load_lds_dwordx4 v134, s[26:27]
	s_mov_b32 m0, s50
	s_nop 0
	global_load_lds_dwordx4 v132, s[26:27]
	s_waitcnt vmcnt(8)
	s_waitcnt lgkmcnt(0)
	s_barrier
	v_mfma_f32_16x16x32_bf16 v[62:65], v[146:149], v[184:187], v[62:65]
	v_mfma_f32_16x16x32_bf16 v[62:65], v[150:153], v[188:191], v[62:65]
	v_mfma_f32_16x16x32_bf16 v[54:57], v[164:167], v[188:191], v[54:57]
	v_mfma_f32_16x16x32_bf16 v[54:57], v[160:163], v[184:187], v[54:57]
	v_mfma_f32_16x16x32_bf16 v[38:41], v[160:163], v[206:209], v[38:41]
	v_mfma_f32_16x16x32_bf16 v[38:41], v[164:167], v[210:213], v[38:41]
	v_mfma_f32_16x16x32_bf16 v[46:49], v[150:153], v[210:213], v[46:49]
	v_mfma_f32_16x16x32_bf16 v[46:49], v[146:149], v[206:209], v[46:49]
	v_mfma_f32_16x16x32_bf16 v[30:33], v[146:149], v[214:217], v[30:33]
	v_mfma_f32_16x16x32_bf16 v[30:33], v[150:153], v[218:221], v[30:33]
	v_mfma_f32_16x16x32_bf16 v[22:25], v[164:167], v[218:221], v[22:25]
	v_mfma_f32_16x16x32_bf16 v[22:25], v[160:163], v[214:217], v[22:25]
	v_mfma_f32_16x16x32_bf16 v[6:9], v[160:163], v[222:225], v[6:9]
	v_mfma_f32_16x16x32_bf16 v[6:9], v[164:167], v[226:229], v[6:9]
	v_mfma_f32_16x16x32_bf16 v[14:17], v[150:153], v[226:229], v[14:17]
	v_mfma_f32_16x16x32_bf16 v[14:17], v[146:149], v[222:225], v[14:17]
	v_mfma_f32_16x16x32_bf16 v[58:61], v[168:171], v[184:187], v[58:61]
	v_mfma_f32_16x16x32_bf16 v[58:61], v[172:175], v[188:191], v[58:61]
	v_mfma_f32_16x16x32_bf16 v[50:53], v[180:183], v[188:191], v[50:53]
	v_mfma_f32_16x16x32_bf16 v[50:53], v[176:179], v[184:187], v[50:53]
	v_mfma_f32_16x16x32_bf16 v[34:37], v[176:179], v[206:209], v[34:37]
	v_mfma_f32_16x16x32_bf16 v[34:37], v[180:183], v[210:213], v[34:37]
	v_mfma_f32_16x16x32_bf16 v[42:45], v[172:175], v[210:213], v[42:45]
	v_mfma_f32_16x16x32_bf16 v[42:45], v[168:171], v[206:209], v[42:45]
	v_mfma_f32_16x16x32_bf16 v[26:29], v[168:171], v[214:217], v[26:29]
	v_mfma_f32_16x16x32_bf16 v[26:29], v[172:175], v[218:221], v[26:29]
	v_mfma_f32_16x16x32_bf16 v[18:21], v[180:183], v[218:221], v[18:21]
	v_mfma_f32_16x16x32_bf16 v[18:21], v[176:179], v[214:217], v[18:21]
	v_mfma_f32_16x16x32_bf16 v[2:5], v[176:179], v[222:225], v[2:5]
	v_mfma_f32_16x16x32_bf16 v[2:5], v[180:183], v[226:229], v[2:5]
	v_mfma_f32_16x16x32_bf16 v[10:13], v[172:175], v[226:229], v[10:13]
	v_mfma_f32_16x16x32_bf16 v[10:13], v[168:171], v[222:225], v[10:13]
	s_barrier
	s_add_i32 s57, s57, 2
	s_add_u32 s55, s55, 0x100
	s_addc_u32 s56, s56, 0
	s_cmp_gt_u32 s57, 13
	s_mov_b64 s[22:23], s[24:25]
	s_cbranch_scc0 .LBB0_409
	s_and_b64 vcc, exec, s[6:7]
	s_cbranch_vccz .LBB0_412
	s_barrier
